# prep phase: second shifted-row load issued together with the first (one exposed round trip less per token tile)
# speedup vs baseline: 1.0055x; 1.0055x over previous
; #define LAS __attribute__((address_space(3)))
; __device__ __forceinline__ unsigned pk2(float lo, float hi) { f32x2 v = {lo, hi}; h16x2 b = __builtin_convertvector(v, h16x2); return __builtin_bit_cast(unsigned, b); }
; __device__ __forceinline__ float bflo(unsigned u) { return (float)__builtin_bit_cast(h16x2, u).x; }
; __device__ __forceinline__ void prep_phase(const Ctx& F, const float* mu, const float* w0, const float* a0, const float* k_k, const float* k_a, const float* r_k) {
;     ...
;         bf16 rin[33], kin[33], vin[33];
;         rin[0] = 0; kin[0] = 0; vin[0] = 0;
;         if (!first0) { const unsigned pb_ = prb - PRWW * 2u; rin[0] = *(const bf16*)((const unsigned char*)PRW + pb_); kin[0] = *(const bf16*)((const unsigned char*)PRW + (pb_ + 1024u)); vin[0] = *(const bf16*)((const unsigned char*)PRW + (pb_ + 2048u)); }
; #pragma unroll
;         for (int t = 0; t < 6; ++t) { rin[t + 1] = PRL(t * PRWW); kin[t + 1] = PRL(t * PRWW + 512); vin[t + 1] = PRL(t * PRWW + 1024); }
;         __syncthreads();
;         float muj[8];
;         { const f32x4 m0 = *(const f32x4*)(mu + 1536 + j0), m1 = *(const f32x4*)(mu + 1540 + j0); muj[0] = m0.x; muj[1] = m0.y; muj[2] = m0.z; muj[3] = m0.w; muj[4] = m1.x; muj[5] = m1.y; muj[6] = m1.z; muj[7] = m1.w; }
; #pragma unroll
;         for (int i = 0; i < 2; ++i) { const int tt = (F.tid >> 5) + 16 * i; const int tok = t0 + tt;
;             const u32x4 pc = *(const u32x4*)(PRW + (size_t)tok * PRWW + 1536 + j0);
;             u32x4 pp = {0u, 0u, 0u, 0u}; if ((tok & (SEQ - 1)) != 0) pp = *(const u32x4*)(PRW + (size_t)(tok - 1) * PRWW + 1536 + j0);
;             float x[8] = {bflo(pc.x), bfhi(pc.x), bflo(pc.y), bfhi(pc.y), bflo(pc.z), bfhi(pc.z), bflo(pc.w), bfhi(pc.w)};
;             const float xp[8] = {bflo(pp.x), bfhi(pp.x), bflo(pp.y), bfhi(pp.y), bflo(pp.z), bfhi(pp.z), bflo(pp.w), bfhi(pp.w)};
; #pragma unroll
;             for (int e = 0; e < 8; ++e) { const float xs = x[e] + (xp[e] - x[e]) * muj[e]; const float y = typ == 0 ? 2.f * xs : xs; const float sg = __builtin_amdgcn_rcpf(1.f + __expf(-y));
;                 x[e] = typ == 0 ? 2.f * sg - 1.f : (typ == 1 ? xs : sg); }
;             u32x4 o; o.x = pk2(x[0], x[1]); o.y = pk2(x[2], x[3]); o.z = pk2(x[4], x[5]); o.w = pk2(x[6], x[7]);
;             *(LAS u32x4*)(act + tt * AP + j0) = o; }
.LBB0_524:
	v_add_u32_e32 v2, 0x400, v229
	v_add_u32_e32 v3, 0x800, v229
	v_add_u32_e32 v4, 0xe00, v229
	v_add_u32_e32 v5, 0x1200, v229
	v_add_u32_e32 v6, 0x1600, v229
	v_add_u32_e32 v7, 0x1c00, v229
	v_add_u32_e32 v8, 0x2000, v229
	global_load_ushort v250, v229, s[12:13]
	global_load_ushort v249, v2, s[12:13]
	global_load_ushort v245, v3, s[12:13]
	global_load_ushort v244, v4, s[12:13]
	global_load_ushort v243, v5, s[12:13]
	global_load_ushort v242, v6, s[12:13]
	global_load_ushort v241, v7, s[12:13]
	global_load_ushort v240, v8, s[12:13]
	v_add_u32_e32 v2, 0x2400, v229
	v_add_u32_e32 v3, 0x2a00, v229
	v_add_u32_e32 v4, 0x2e00, v229
	v_add_u32_e32 v5, 0x3200, v229
	v_add_u32_e32 v6, 0x3800, v229
	v_add_u32_e32 v7, 0x3c00, v229
	v_add_u32_e32 v8, 0x4000, v229
	v_add_u32_e32 v9, 0x4600, v229
	global_load_ushort v239, v2, s[12:13]
	global_load_ushort v238, v3, s[12:13]
	global_load_ushort v237, v4, s[12:13]
	global_load_ushort v236, v5, s[12:13]
	global_load_ushort v235, v6, s[12:13]
	global_load_ushort v234, v7, s[12:13]
	global_load_ushort v233, v8, s[12:13]
	global_load_ushort v232, v9, s[12:13]
	v_add_u32_e32 v24, s36, v226
	v_add_u32_e32 v2, 0x4a00, v229
	v_add_u32_e32 v3, 0x4e00, v229
	v_mad_i64_i32 v[6:7], s[26:27], v24, s39, v[154:155]
	global_load_ushort v231, v2, s[12:13]
	global_load_ushort v230, v3, s[12:13]
	s_barrier
	global_load_dwordx4 v[2:5], v[140:141], off offset:16
	global_load_dwordx4 v[10:13], v[140:141], off
	global_load_dwordx4 v[16:19], v[6:7], off offset:3072
	v_add_u32_e32 v40, 15, v24
	v_mad_i64_i32 v[38:39], s[42:43], v40, s39, v[154:155]
	global_load_dwordx4 v[34:37], v[38:39], off offset:3072
	v_and_b32_e32 v6, 0xfff, v24
	v_cmp_ne_u32_e32 vcc, 0, v6
	v_mov_b32_e32 v6, 0
	v_mov_b32_e32 v20, 0
	v_mov_b32_e32 v21, 0
	v_mov_b32_e32 v22, 0
	v_mov_b32_e32 v23, 0
	s_and_saveexec_b64 s[26:27], vcc
	s_cbranch_execz .LBB0_526
	v_add_u32_e32 v7, -1, v24
	v_mad_i64_i32 v[8:9], s[42:43], v7, s39, v[154:155]
	global_load_dwordx4 v[20:23], v[8:9], off offset:3072
.LBB0_526:
	s_or_b64 exec, exec, s[26:27]
	s_waitcnt vmcnt(0)
	v_cvt_f32_f16_e32 v7, v16
	v_cvt_f32_f16_e32 v8, v20
	v_cvt_f32_f16_sdwa v9, v16 dst_sel:DWORD dst_unused:UNUSED_PAD src0_sel:WORD_1
	v_cvt_f32_f16_sdwa v14, v20 dst_sel:DWORD dst_unused:UNUSED_PAD src0_sel:WORD_1
	v_add_u32_e32 v32, 16, v24
	v_sub_f32_e32 v7, v8, v7
	v_fma_mix_f32 v7, v10, v7, v16 op_sel_hi:[0,0,1]
	v_add_f32_e32 v8, v7, v7
	v_cndmask_b32_e64 v8, v8, v7, s[10:11]
	v_mul_f32_e32 v8, 0xbfb8aa3b, v8
	v_exp_f32_e32 v8, v8
	v_sub_f32_e32 v9, v14, v9
	v_fma_mix_f32 v25, v11, v9, v16 op_sel:[0,0,1] op_sel_hi:[0,0,1]
	v_add_f32_e32 v9, v25, v25
	v_cndmask_b32_e64 v9, v9, v25, s[10:11]
	v_add_f32_e32 v8, 1.0, v8
	v_mul_f32_e32 v9, 0xbfb8aa3b, v9
	v_rcp_f32_e32 v8, v8
	v_exp_f32_e32 v9, v9
	v_mad_i64_i32 v[14:15], s[26:27], v32, s39, v[154:155]
	v_fma_f32 v20, v8, 2.0, -1.0
	v_cndmask_b32_e64 v7, v8, v7, s[4:5]
	v_add_f32_e32 v8, 1.0, v9
	v_rcp_f32_e32 v28, v8
	v_cvt_f32_f16_sdwa v9, v17 dst_sel:DWORD dst_unused:UNUSED_PAD src0_sel:WORD_1
	v_cvt_f32_f16_e32 v8, v17
	global_load_dwordx4 v[14:17], v[14:15], off offset:3072
	v_cvt_f32_f16_sdwa v27, v21 dst_sel:DWORD dst_unused:UNUSED_PAD src0_sel:WORD_1
	v_cvt_f32_f16_e32 v26, v21
	v_cndmask_b32_e64 v7, v20, v7, s[10:11]
	v_fma_f32 v30, v28, 2.0, -1.0
	v_cndmask_b32_e64 v25, v28, v25, s[4:5]
	v_pk_add_f32 v[20:21], v[26:27], v[8:9] neg_lo:[0,1] neg_hi:[0,1]
	v_cvt_f32_f16_sdwa v27, v18 dst_sel:DWORD dst_unused:UNUSED_PAD src0_sel:WORD_1
	v_pk_fma_f32 v[8:9], v[12:13], v[20:21], v[8:9]
	v_cvt_f32_f16_e32 v26, v18
	v_cvt_f32_f16_sdwa v29, v22 dst_sel:DWORD dst_unused:UNUSED_PAD src0_sel:WORD_1
	v_cvt_f32_f16_e32 v28, v22
	v_add_f32_e32 v20, v8, v8
	v_add_f32_e32 v21, v9, v9
	v_cndmask_b32_e64 v20, v20, v8, s[10:11]
	v_cndmask_b32_e64 v21, v21, v9, s[10:11]
	v_mul_f32_e32 v20, 0xbfb8aa3b, v20
	v_mul_f32_e32 v21, 0xbfb8aa3b, v21
	v_exp_f32_e32 v20, v20
	v_exp_f32_e32 v21, v21
	v_pk_add_f32 v[28:29], v[28:29], v[26:27] neg_lo:[0,1] neg_hi:[0,1]
	v_cndmask_b32_e64 v25, v30, v25, s[10:11]
	v_pk_fma_f32 v[26:27], v[2:3], v[28:29], v[26:27]
	v_add_f32_e32 v20, 1.0, v20
	v_add_f32_e32 v18, v27, v27
	v_cndmask_b32_e64 v18, v18, v27, s[10:11]
	v_add_f32_e32 v21, 1.0, v21
	v_mul_f32_e32 v18, 0xbfb8aa3b, v18
	v_rcp_f32_e32 v20, v20
	v_rcp_f32_e32 v21, v21
	v_exp_f32_e32 v18, v18
	v_cndmask_b32_e64 v22, v20, v8, s[4:5]
	v_pk_fma_f32 v[30:31], v[20:21], 2.0, -1.0 op_sel_hi:[1,0,0]
	v_cndmask_b32_e64 v28, v21, v9, s[4:5]
	v_add_f32_e32 v9, 1.0, v18
	v_cvt_f32_f16_sdwa v21, v19 dst_sel:DWORD dst_unused:UNUSED_PAD src0_sel:WORD_1
	v_cvt_f32_f16_e32 v20, v19
	v_cvt_f32_f16_sdwa v19, v23 dst_sel:DWORD dst_unused:UNUSED_PAD src0_sel:WORD_1
	v_cvt_f32_f16_e32 v18, v23
	v_add_f32_e32 v8, v26, v26
	v_cndmask_b32_e64 v8, v8, v26, s[10:11]
	v_mul_f32_e32 v8, 0xbfb8aa3b, v8
	v_pk_add_f32 v[18:19], v[18:19], v[20:21] neg_lo:[0,1] neg_hi:[0,1]
	v_exp_f32_e32 v8, v8
	v_pk_fma_f32 v[18:19], v[4:5], v[18:19], v[20:21]
	v_rcp_f32_e32 v9, v9
	v_add_f32_e32 v20, v18, v18
	v_add_f32_e32 v21, v19, v19
	v_cndmask_b32_e64 v20, v20, v18, s[10:11]
	v_cndmask_b32_e64 v21, v21, v19, s[10:11]
	v_mul_f32_e32 v20, 0xbfb8aa3b, v20
	v_mul_f32_e32 v21, 0xbfb8aa3b, v21
	v_exp_f32_e32 v20, v20
	v_exp_f32_e32 v21, v21
	v_add_f32_e32 v8, 1.0, v8
	v_rcp_f32_e32 v8, v8
	v_add_f32_e32 v20, 1.0, v20
	v_add_f32_e32 v21, 1.0, v21
	v_rcp_f32_e32 v20, v20
	v_rcp_f32_e32 v21, v21
	v_cndmask_b32_e64 v29, v30, v22, s[10:11]
	v_pk_fma_f32 v[22:23], v[8:9], 2.0, -1.0 op_sel_hi:[1,0,0]
	v_cndmask_b32_e64 v8, v8, v26, s[4:5]
	v_cndmask_b32_e64 v9, v9, v27, s[4:5]
	v_cndmask_b32_e64 v23, v23, v9, s[10:11]
	v_cndmask_b32_e64 v22, v22, v8, s[10:11]
	v_pk_fma_f32 v[8:9], v[20:21], 2.0, -1.0 op_sel_hi:[1,0,0]
	v_cndmask_b32_e64 v18, v20, v18, s[4:5]
	v_cndmask_b32_e64 v19, v21, v19, s[4:5]
	v_cndmask_b32_e64 v28, v31, v28, s[10:11]
	v_cndmask_b32_e64 v9, v9, v19, s[10:11]
	v_cndmask_b32_e64 v8, v8, v18, s[10:11]
	v_cvt_pk_f16_f32 v18, v7, v25
	v_and_b32_e32 v7, 0xfff, v32
	v_cvt_pk_f16_f32 v19, v29, v28
	v_cvt_pk_f16_f32 v20, v22, v23
	v_cvt_pk_f16_f32 v21, v8, v9
	v_cmp_ne_u32_e32 vcc, 0, v7
	v_mov_b32_e32 v7, 0
	v_mov_b32_e32 v8, 0
	v_mov_b32_e32 v9, 0
	ds_write_b128 v227, v[18:21]
	s_and_saveexec_b64 s[26:27], vcc
	s_cbranch_execz .LBB0_528
	v_mov_b32_e32 v6, v34
	v_mov_b32_e32 v7, v35
	v_mov_b32_e32 v8, v36
	v_mov_b32_e32 v9, v37
